# v26 + sc1 (write-through) on the P1 epilogue tile stores
# baseline (speedup 1.0000x reference)
;     __device__ __forceinline__ void operator()(const pg8::f32x4 (&acc)[2][2][4][2], const Unit& u, int wr, int wc, int fr, int fq) const {
;     ...
;         } else { const int col0 = (u.pn - 8) * BM + wc * 32 + 8 * fq;
; #pragma unroll
;             for (int ai = 0; ai < 2; ++ai)
; #pragma unroll
;                 for (int m = 0; m < 4; ++m) { float* rowp = FZ + (size_t)(row0 + ai * HALF + m * 16) * 512 + col0;
; #pragma unroll
;                     for (int bj = 0; bj < 2; ++bj)
; #pragma unroll
;                         for (int n = 0; n < 2; ++n) *(pg8::f32x4*)(rowp + bj * HALF + 4 * n) = acc[ai][bj][m][n]; }
.LBB0_140:
	v_lshl_add_u32 v150, s20, 8, v156
	s_cmp_gt_i32 s44, 1
	v_ashrrev_i32_e32 v151, 31, v150
	s_mov_b64 s[20:21], -1
	s_cbranch_scc0 .LBB0_147
	s_lshl_b32 s13, s44, 8
	s_cmp_gt_u32 s44, 7
	s_cbranch_scc0 .LBB0_143
	v_or_b32_e32 v166, 16, v150
	v_readlane_b32 s20, v238, 45
	v_ashrrev_i32_e32 v167, 31, v166
	v_add_u32_e32 v138, s13, v159
	v_lshlrev_b64 v[152:153], 11, v[150:151]
	v_readlane_b32 s21, v238, 46
	v_lshlrev_b64 v[166:167], 11, v[166:167]
	v_lshlrev_b64 v[164:165], 2, v[138:139]
	v_lshl_add_u64 v[152:153], s[20:21], 0, v[152:153]
	v_lshl_add_u64 v[166:167], s[20:21], 0, v[166:167]
	v_lshl_add_u64 v[152:153], v[152:153], 0, v[164:165]
	v_lshl_add_u64 v[166:167], v[166:167], 0, v[164:165]
	global_store_dwordx4 v[152:153], v[126:129], off sc1
	global_store_dwordx4 v[152:153], v[122:125], off offset:16 sc1
	global_store_dwordx4 v[152:153], v[118:121], off offset:512 sc1
	global_store_dwordx4 v[152:153], v[110:113], off offset:528 sc1
	global_store_dwordx4 v[166:167], v[114:117], off sc1
	global_store_dwordx4 v[166:167], v[106:109], off offset:16 sc1
	global_store_dwordx4 v[166:167], v[98:101], off offset:512 sc1
	global_store_dwordx4 v[166:167], v[90:93], off offset:528 sc1
	v_or_b32_e32 v166, 32, v150
	v_ashrrev_i32_e32 v167, 31, v166
	v_lshlrev_b64 v[166:167], 11, v[166:167]
	v_lshl_add_u64 v[166:167], s[20:21], 0, v[166:167]
	v_lshl_add_u64 v[166:167], v[166:167], 0, v[164:165]
	global_store_dwordx4 v[166:167], v[102:105], off sc1
	global_store_dwordx4 v[166:167], v[94:97], off offset:16 sc1
	global_store_dwordx4 v[166:167], v[82:85], off offset:512 sc1
	global_store_dwordx4 v[166:167], v[74:77], off offset:528 sc1
	v_or_b32_e32 v166, 48, v150
	v_ashrrev_i32_e32 v167, 31, v166
	v_lshlrev_b64 v[166:167], 11, v[166:167]
	v_lshl_add_u64 v[166:167], s[20:21], 0, v[166:167]
	s_mov_b32 s15, 0x40000
	v_lshl_add_u64 v[164:165], v[166:167], 0, v[164:165]
	v_add_co_u32_e32 v166, vcc, s15, v152
	s_mov_b64 s[20:21], 0x40000
	s_nop 0
	v_addc_co_u32_e32 v167, vcc, 0, v153, vcc
	s_mov_b32 s15, 0x48000
	global_store_dwordx4 v[164:165], v[86:89], off sc1
	global_store_dwordx4 v[164:165], v[78:81], off offset:16 sc1
	global_store_dwordx4 v[164:165], v[70:73], off offset:512 sc1
	global_store_dwordx4 v[164:165], v[66:69], off offset:528 sc1
	v_lshl_add_u64 v[164:165], v[152:153], 0, s[20:21]
	global_store_dwordx4 v[166:167], v[62:65], off sc1
	global_store_dwordx4 v[164:165], v[58:61], off offset:16 sc1
	global_store_dwordx4 v[164:165], v[50:53], off offset:512 sc1
	global_store_dwordx4 v[164:165], v[42:45], off offset:528 sc1
	v_add_co_u32_e32 v166, vcc, s15, v152
	s_mov_b64 s[20:21], 0x48000
	s_nop 0
	v_addc_co_u32_e32 v167, vcc, 0, v153, vcc
	s_mov_b32 s15, 0x50000
	v_lshl_add_u64 v[164:165], v[152:153], 0, s[20:21]
	global_store_dwordx4 v[166:167], v[54:57], off sc1
	global_store_dwordx4 v[164:165], v[46:49], off offset:16 sc1
	global_store_dwordx4 v[164:165], v[34:37], off offset:512 sc1
	global_store_dwordx4 v[164:165], v[26:29], off offset:528 sc1
	s_mov_b64 s[20:21], 0x50000
	v_add_co_u32_e32 v166, vcc, s15, v152
	v_lshl_add_u64 v[164:165], v[152:153], 0, s[20:21]
	s_nop 0
	v_addc_co_u32_e32 v167, vcc, 0, v153, vcc
	s_mov_b64 s[20:21], 0x58000
	global_store_dwordx4 v[166:167], v[38:41], off sc1
	global_store_dwordx4 v[164:165], v[30:33], off offset:16 sc1
	global_store_dwordx4 v[164:165], v[18:21], off offset:512 sc1
	global_store_dwordx4 v[164:165], v[10:13], off offset:528 sc1
	v_lshl_add_u64 v[164:165], v[152:153], 0, s[20:21]
	v_add_co_u32_e32 v152, vcc, 0x58000, v152
	s_mov_b64 s[20:21], 0
	s_nop 0
	v_addc_co_u32_e32 v153, vcc, 0, v153, vcc
	global_store_dwordx4 v[152:153], v[22:25], off sc1
	global_store_dwordx4 v[164:165], v[14:17], off offset:16 sc1
	global_store_dwordx4 v[164:165], v[6:9], off offset:512 sc1
	global_store_dwordx4 v[164:165], v[2:5], off offset:528 sc1
; __device__ __forceinline__ unsigned cvt_pk_bf16(float lo, float hi) { unsigned r; asm volatile("v_cvt_pk_bf16_f32 %0, %1, %2" : "=v"(r) : "v"(lo), "v"(hi)); return r; }
;     __device__ __forceinline__ void operator()(const pg8::f32x4 (&acc)[2][2][4][2], const Unit& u, int wr, int wc, int fr, int fq) const {
;     ...
;         } else if (u.pn < 8) { const int col0 = u.pn * BM + wc * 32 + 8 * fq;
; #pragma unroll
;             for (int ai = 0; ai < 2; ++ai)
; #pragma unroll
;                 for (int m = 0; m < 4; ++m) { bf16* rowp = PB + (size_t)(row0 + ai * HALF + m * 16) * PBW + col0;
; #pragma unroll
;                     for (int bj = 0; bj < 2; ++bj) { const pg8::f32x4 v0 = acc[ai][bj][m][0], v1 = acc[ai][bj][m][1]; u32x4 w; w.x = cvt_pk_bf16(v0[0], v0[1]); w.y = cvt_pk_bf16(v0[2], v0[3]); w.z = cvt_pk_bf16(v1[0], v1[1]); w.w = cvt_pk_bf16(v1[2], v1[3]);
;                         *(u32x4*)(rowp + bj * HALF) = w; } }
.LBB0_143:
	s_andn2_b64 vcc, exec, s[20:21]
	s_cbranch_vccnz .LBB0_145
	v_or_b32_e32 v138, s13, v158
	v_lshlrev_b64 v[152:153], 12, v[150:151]
	v_lshl_add_u64 v[152:153], s[56:57], 0, v[152:153]
	v_lshlrev_b32_e32 v138, 1, v138
	v_lshl_add_u64 v[152:153], v[152:153], 0, v[138:139]
	v_cvt_pk_bf16_f32 v164, v126, v127
	v_cvt_pk_bf16_f32 v165, v128, v129
	v_cvt_pk_bf16_f32 v166, v122, v123
	v_cvt_pk_bf16_f32 v167, v124, v125
	global_store_dwordx4 v[152:153], v[164:167], off sc1
	s_mov_b32 s13, 0x80000
	v_add_co_u32_e32 v170, vcc, s13, v152
	v_cvt_pk_bf16_f32 v164, v118, v119
	v_cvt_pk_bf16_f32 v165, v120, v121
	v_cvt_pk_bf16_f32 v166, v110, v111
	v_cvt_pk_bf16_f32 v167, v112, v113
	global_store_dwordx4 v[152:153], v[164:167], off offset:256 sc1
	s_mov_b64 s[20:21], 0x80000
	v_addc_co_u32_e32 v171, vcc, 0, v153, vcc
	v_or_b32_e32 v164, 16, v150
	v_ashrrev_i32_e32 v165, 31, v164
	v_lshlrev_b64 v[164:165], 12, v[164:165]
	v_lshl_add_u64 v[164:165], s[56:57], 0, v[164:165]
	v_lshl_add_u64 v[168:169], v[164:165], 0, v[138:139]
	v_cvt_pk_bf16_f32 v164, v114, v115
	v_cvt_pk_bf16_f32 v165, v116, v117
	v_cvt_pk_bf16_f32 v166, v106, v107
	v_cvt_pk_bf16_f32 v167, v108, v109
	global_store_dwordx4 v[168:169], v[164:167], off sc1
	s_mov_b32 s13, 0x90000
	s_nop 0
	v_cvt_pk_bf16_f32 v164, v98, v99
	v_cvt_pk_bf16_f32 v165, v100, v101
	v_cvt_pk_bf16_f32 v166, v90, v91
	v_cvt_pk_bf16_f32 v167, v92, v93
	global_store_dwordx4 v[168:169], v[164:167], off offset:256 sc1
	s_nop 1
	v_or_b32_e32 v164, 32, v150
	v_ashrrev_i32_e32 v165, 31, v164
	v_lshlrev_b64 v[164:165], 12, v[164:165]
	v_lshl_add_u64 v[164:165], s[56:57], 0, v[164:165]
	v_lshl_add_u64 v[168:169], v[164:165], 0, v[138:139]
	v_cvt_pk_bf16_f32 v164, v102, v103
	v_cvt_pk_bf16_f32 v165, v104, v105
	v_cvt_pk_bf16_f32 v166, v94, v95
	v_cvt_pk_bf16_f32 v167, v96, v97
	global_store_dwordx4 v[168:169], v[164:167], off sc1
	s_nop 1
	v_cvt_pk_bf16_f32 v164, v82, v83
	v_cvt_pk_bf16_f32 v165, v84, v85
	v_cvt_pk_bf16_f32 v166, v74, v75
	v_cvt_pk_bf16_f32 v167, v76, v77
	global_store_dwordx4 v[168:169], v[164:167], off offset:256 sc1
	s_nop 1
	v_or_b32_e32 v164, 48, v150
	v_ashrrev_i32_e32 v165, 31, v164
	v_lshlrev_b64 v[164:165], 12, v[164:165]
	v_lshl_add_u64 v[164:165], s[56:57], 0, v[164:165]
	v_lshl_add_u64 v[168:169], v[164:165], 0, v[138:139]
	v_cvt_pk_bf16_f32 v164, v86, v87
	v_cvt_pk_bf16_f32 v165, v88, v89
	v_cvt_pk_bf16_f32 v166, v78, v79
	v_cvt_pk_bf16_f32 v167, v80, v81
	global_store_dwordx4 v[168:169], v[164:167], off sc1
	s_nop 1
	v_cvt_pk_bf16_f32 v164, v70, v71
	v_cvt_pk_bf16_f32 v165, v72, v73
	v_cvt_pk_bf16_f32 v166, v66, v67
	v_cvt_pk_bf16_f32 v167, v68, v69
	global_store_dwordx4 v[168:169], v[164:167], off offset:256 sc1
	v_lshl_add_u64 v[168:169], v[152:153], 0, s[20:21]
	s_mov_b64 s[20:21], 0x90000
	v_cvt_pk_bf16_f32 v164, v62, v63
	v_cvt_pk_bf16_f32 v165, v64, v65
	v_cvt_pk_bf16_f32 v166, v58, v59
	v_cvt_pk_bf16_f32 v167, v60, v61
	global_store_dwordx4 v[170:171], v[164:167], off sc1
	v_add_co_u32_e32 v170, vcc, s13, v152
	s_nop 0
	v_cvt_pk_bf16_f32 v164, v50, v51
	v_cvt_pk_bf16_f32 v165, v52, v53
	v_cvt_pk_bf16_f32 v166, v42, v43
	v_cvt_pk_bf16_f32 v167, v44, v45
	global_store_dwordx4 v[168:169], v[164:167], off offset:256 sc1
	v_addc_co_u32_e32 v171, vcc, 0, v153, vcc
	s_nop 0
	v_cvt_pk_bf16_f32 v164, v54, v55
	v_cvt_pk_bf16_f32 v165, v56, v57
	v_cvt_pk_bf16_f32 v166, v46, v47
	v_cvt_pk_bf16_f32 v167, v48, v49
	s_mov_b32 s13, 0xa0000
	v_lshl_add_u64 v[168:169], v[152:153], 0, s[20:21]
	global_store_dwordx4 v[170:171], v[164:167], off sc1
	s_mov_b64 s[20:21], 0xa0000
	v_add_co_u32_e32 v170, vcc, s13, v152
	v_cvt_pk_bf16_f32 v164, v34, v35
	v_cvt_pk_bf16_f32 v165, v36, v37
	v_cvt_pk_bf16_f32 v166, v26, v27
	v_cvt_pk_bf16_f32 v167, v28, v29
	global_store_dwordx4 v[168:169], v[164:167], off offset:256 sc1
	v_lshl_add_u64 v[168:169], v[152:153], 0, s[20:21]
	v_addc_co_u32_e32 v171, vcc, 0, v153, vcc
	v_cvt_pk_bf16_f32 v164, v38, v39
	v_cvt_pk_bf16_f32 v165, v40, v41
	v_cvt_pk_bf16_f32 v166, v30, v31
	v_cvt_pk_bf16_f32 v167, v32, v33
	s_mov_b64 s[20:21], 0xb0000
	s_mov_b32 s13, 0xb0000
	global_store_dwordx4 v[170:171], v[164:167], off sc1
	s_nop 1
	v_cvt_pk_bf16_f32 v164, v18, v19
	v_cvt_pk_bf16_f32 v165, v20, v21
	v_cvt_pk_bf16_f32 v166, v10, v11
	v_cvt_pk_bf16_f32 v167, v12, v13
	global_store_dwordx4 v[168:169], v[164:167], off offset:256 sc1
	v_lshl_add_u64 v[168:169], v[152:153], 0, s[20:21]
	v_add_co_u32_e32 v152, vcc, s13, v152
	v_cvt_pk_bf16_f32 v164, v22, v23
	v_cvt_pk_bf16_f32 v165, v24, v25
	v_cvt_pk_bf16_f32 v166, v14, v15
	v_cvt_pk_bf16_f32 v167, v16, v17
	s_nop 1
	v_addc_co_u32_e32 v153, vcc, 0, v153, vcc
	global_store_dwordx4 v[152:153], v[164:167], off sc1
	s_nop 1
	v_cvt_pk_bf16_f32 v164, v6, v7
	v_cvt_pk_bf16_f32 v165, v8, v9
	v_cvt_pk_bf16_f32 v166, v2, v3
	v_cvt_pk_bf16_f32 v167, v4, v5
	global_store_dwordx4 v[168:169], v[164:167], off offset:256 sc1

; __device__ __forceinline__ unsigned cvt_pk_bf16(float lo, float hi) { unsigned r; asm volatile("v_cvt_pk_bf16_f32 %0, %1, %2" : "=v"(r) : "v"(lo), "v"(hi)); return r; }
;     __device__ __forceinline__ void operator()(const pg8::f32x4 (&acc)[2][2][4][2], const Unit& u, int wr, int wc, int fr, int fq) const {
;     ...
;         if (u.pn < 2) { const int col0 = u.pn * BM + wc * 32 + 8 * fq;
; #pragma unroll
;             for (int ai = 0; ai < 2; ++ai)
; #pragma unroll
;                 for (int m = 0; m < 4; ++m) { const size_t r = (size_t)(row0 + ai * HALF + m * 16);
; #pragma unroll
;                     for (int bj = 0; bj < 2; ++bj) { const int col = col0 + bj * HALF; const pg8::f32x4 v0 = acc[ai][bj][m][0], v1 = acc[ai][bj][m][1]; u32x4 w; w.x = cvt_pk_bf16(v0[0], v0[1]); w.y = cvt_pk_bf16(v0[2], v0[3]); w.z = cvt_pk_bf16(v1[0], v1[1]); w.w = cvt_pk_bf16(v1[2], v1[3]);
;                         *(u32x4*)(U5 + ((size_t)(col >> 4) * MTOK + r) * 16 + (col & 15)) = w; } }
.LBB0_148:
	v_lshl_or_b32 v138, s44, 8, v158
	v_cvt_pk_bf16_f32 v126, v126, v127
	v_cvt_pk_bf16_f32 v127, v128, v129
	v_cvt_pk_bf16_f32 v128, v122, v123
	v_cvt_pk_bf16_f32 v129, v124, v125
	v_ashrrev_i32_e32 v124, 4, v138
	v_mad_i64_i32 v[122:123], s[20:21], v124, s43, v[150:151]
	v_lshlrev_b64 v[122:123], 5, v[122:123]
	v_lshl_add_u64 v[122:123], v[140:141], 0, v[122:123]
	global_store_dwordx4 v[122:123], v[126:129], off sc1
	v_or_b32_e32 v122, 8, v124
	v_cvt_pk_bf16_f32 v118, v118, v119
	v_cvt_pk_bf16_f32 v119, v120, v121
	v_cvt_pk_bf16_f32 v120, v110, v111
	v_mad_i64_i32 v[110:111], s[20:21], v122, s43, v[150:151]
	v_lshlrev_b64 v[110:111], 5, v[110:111]
	v_lshl_add_u64 v[110:111], v[140:141], 0, v[110:111]
	v_cvt_pk_bf16_f32 v121, v112, v113
	global_store_dwordx4 v[110:111], v[118:121], off sc1
	v_cvt_pk_bf16_f32 v110, v114, v115
	v_cvt_pk_bf16_f32 v111, v116, v117
	v_cvt_pk_bf16_f32 v112, v106, v107
	v_cvt_pk_bf16_f32 v113, v108, v109
	s_nop 1
	v_or_b32_e32 v118, 16, v150
	v_ashrrev_i32_e32 v119, 31, v118
	v_mad_i64_i32 v[106:107], s[20:21], v124, s43, v[118:119]
	v_lshlrev_b64 v[106:107], 5, v[106:107]
	v_lshl_add_u64 v[106:107], v[140:141], 0, v[106:107]
	global_store_dwordx4 v[106:107], v[110:113], off sc1
	v_cvt_pk_bf16_f32 v98, v98, v99
	v_cvt_pk_bf16_f32 v99, v100, v101
	v_cvt_pk_bf16_f32 v100, v90, v91
	v_mad_i64_i32 v[90:91], s[20:21], v122, s43, v[118:119]
	v_lshlrev_b64 v[90:91], 5, v[90:91]
	v_lshl_add_u64 v[90:91], v[140:141], 0, v[90:91]
	v_cvt_pk_bf16_f32 v101, v92, v93
	global_store_dwordx4 v[90:91], v[98:101], off sc1
	v_cvt_pk_bf16_f32 v90, v102, v103
	v_cvt_pk_bf16_f32 v91, v104, v105
	v_cvt_pk_bf16_f32 v92, v94, v95
	v_cvt_pk_bf16_f32 v93, v96, v97
	s_nop 1
	v_or_b32_e32 v98, 32, v150
	v_ashrrev_i32_e32 v99, 31, v98
	v_mad_i64_i32 v[94:95], s[20:21], v124, s43, v[98:99]
	v_lshlrev_b64 v[94:95], 5, v[94:95]
	v_lshl_add_u64 v[94:95], v[140:141], 0, v[94:95]
	global_store_dwordx4 v[94:95], v[90:93], off sc1
	v_cvt_pk_bf16_f32 v82, v82, v83
	v_cvt_pk_bf16_f32 v83, v84, v85
	v_cvt_pk_bf16_f32 v84, v74, v75
	v_mad_i64_i32 v[74:75], s[20:21], v122, s43, v[98:99]
	v_lshlrev_b64 v[74:75], 5, v[74:75]
	v_lshl_add_u64 v[74:75], v[140:141], 0, v[74:75]
	v_cvt_pk_bf16_f32 v85, v76, v77
	global_store_dwordx4 v[74:75], v[82:85], off sc1
	v_cvt_pk_bf16_f32 v74, v86, v87
	v_cvt_pk_bf16_f32 v75, v88, v89
	v_cvt_pk_bf16_f32 v76, v78, v79
	v_cvt_pk_bf16_f32 v77, v80, v81
	s_nop 1
	v_or_b32_e32 v82, 48, v150
	v_ashrrev_i32_e32 v83, 31, v82
	v_mad_i64_i32 v[78:79], s[20:21], v124, s43, v[82:83]
	v_lshlrev_b64 v[78:79], 5, v[78:79]
	v_lshl_add_u64 v[78:79], v[140:141], 0, v[78:79]
	global_store_dwordx4 v[78:79], v[74:77], off sc1
	v_cvt_pk_bf16_f32 v70, v70, v71
	v_cvt_pk_bf16_f32 v71, v72, v73
	v_cvt_pk_bf16_f32 v72, v66, v67
	v_mad_i64_i32 v[66:67], s[20:21], v122, s43, v[82:83]
	v_lshlrev_b64 v[66:67], 5, v[66:67]
	v_lshl_add_u64 v[66:67], v[140:141], 0, v[66:67]
	v_cvt_pk_bf16_f32 v73, v68, v69
	global_store_dwordx4 v[66:67], v[70:73], off sc1
	v_add_u32_e32 v66, 0x80, v150
	v_ashrrev_i32_e32 v67, 31, v66
	v_cvt_pk_bf16_f32 v62, v62, v63
	v_cvt_pk_bf16_f32 v63, v64, v65
	v_cvt_pk_bf16_f32 v64, v58, v59
	v_mad_i64_i32 v[58:59], s[20:21], v124, s43, v[66:67]
	v_lshlrev_b64 v[58:59], 5, v[58:59]
	v_lshl_add_u64 v[58:59], v[140:141], 0, v[58:59]
	v_cvt_pk_bf16_f32 v65, v60, v61
	global_store_dwordx4 v[58:59], v[62:65], off sc1
	v_cvt_pk_bf16_f32 v50, v50, v51
	v_cvt_pk_bf16_f32 v51, v52, v53
	v_cvt_pk_bf16_f32 v52, v42, v43
	v_mad_i64_i32 v[42:43], s[20:21], v122, s43, v[66:67]
	v_lshlrev_b64 v[42:43], 5, v[42:43]
	v_lshl_add_u64 v[42:43], v[140:141], 0, v[42:43]
	v_cvt_pk_bf16_f32 v53, v44, v45
	global_store_dwordx4 v[42:43], v[50:53], off sc1
	v_cvt_pk_bf16_f32 v42, v54, v55
	v_cvt_pk_bf16_f32 v43, v56, v57
	v_cvt_pk_bf16_f32 v44, v46, v47
	v_cvt_pk_bf16_f32 v45, v48, v49
	s_nop 1
	v_add_u32_e32 v50, 0x90, v150
	v_ashrrev_i32_e32 v51, 31, v50
	v_mad_i64_i32 v[46:47], s[20:21], v124, s43, v[50:51]
	v_lshlrev_b64 v[46:47], 5, v[46:47]
	v_lshl_add_u64 v[46:47], v[140:141], 0, v[46:47]
	global_store_dwordx4 v[46:47], v[42:45], off sc1
	v_cvt_pk_bf16_f32 v34, v34, v35
	v_cvt_pk_bf16_f32 v35, v36, v37
	v_cvt_pk_bf16_f32 v36, v26, v27
	v_mad_i64_i32 v[26:27], s[20:21], v122, s43, v[50:51]
	v_lshlrev_b64 v[26:27], 5, v[26:27]
	v_lshl_add_u64 v[26:27], v[140:141], 0, v[26:27]
	v_cvt_pk_bf16_f32 v37, v28, v29
	global_store_dwordx4 v[26:27], v[34:37], off sc1
	v_cvt_pk_bf16_f32 v26, v38, v39
	v_cvt_pk_bf16_f32 v27, v40, v41
	v_cvt_pk_bf16_f32 v28, v30, v31
	v_cvt_pk_bf16_f32 v29, v32, v33
	s_nop 1
	v_add_u32_e32 v34, 0xa0, v150
	v_ashrrev_i32_e32 v35, 31, v34
	v_mad_i64_i32 v[30:31], s[20:21], v124, s43, v[34:35]
	v_lshlrev_b64 v[30:31], 5, v[30:31]
	v_lshl_add_u64 v[30:31], v[140:141], 0, v[30:31]
	global_store_dwordx4 v[30:31], v[26:29], off sc1
	v_cvt_pk_bf16_f32 v18, v18, v19
	v_cvt_pk_bf16_f32 v19, v20, v21
	v_cvt_pk_bf16_f32 v20, v10, v11
	v_mad_i64_i32 v[10:11], s[20:21], v122, s43, v[34:35]
	v_lshlrev_b64 v[10:11], 5, v[10:11]
	v_lshl_add_u64 v[10:11], v[140:141], 0, v[10:11]
	v_cvt_pk_bf16_f32 v21, v12, v13
	global_store_dwordx4 v[10:11], v[18:21], off sc1
	v_cvt_pk_bf16_f32 v10, v22, v23
	v_cvt_pk_bf16_f32 v11, v24, v25
	v_cvt_pk_bf16_f32 v12, v14, v15
	v_cvt_pk_bf16_f32 v13, v16, v17
	s_nop 1
	v_add_u32_e32 v18, 0xb0, v150
	v_ashrrev_i32_e32 v19, 31, v18
	v_mad_i64_i32 v[14:15], s[20:21], v124, s43, v[18:19]
	v_lshlrev_b64 v[14:15], 5, v[14:15]
	v_lshl_add_u64 v[14:15], v[140:141], 0, v[14:15]
	global_store_dwordx4 v[14:15], v[10:13], off sc1
	v_cvt_pk_bf16_f32 v6, v6, v7
	v_cvt_pk_bf16_f32 v7, v8, v9
	v_cvt_pk_bf16_f32 v8, v2, v3
	v_mad_i64_i32 v[2:3], s[20:21], v122, s43, v[18:19]
	v_lshlrev_b64 v[2:3], 5, v[2:3]
	v_lshl_add_u64 v[2:3], v[140:141], 0, v[2:3]
	v_cvt_pk_bf16_f32 v9, v4, v5
	global_store_dwordx4 v[2:3], v[6:9], off sc1
	s_andn2_b64 vcc, exec, s[0:1]
	s_mov_b64 s[0:1], -1
	s_cbranch_vccnz .LBB0_133
